# speedup vs baseline: 1.0103x; 1.0103x over previous
; template <int DH, int MODE>
; __device__ void attn_item(const Params& p, int layer, int b, int blk, int head, char* smem) {
;     ...
;     V_SCATTER_(vr0, 0);
;     V_SCATTER_(vr1, 1);
;     if (KCH > 2) {
;       V_SCATTER_(vr2, 2);
;       V_SCATTER_(vr3, 3);
;     }
;     KV_LOAD_(it + 1);
;     if (!wskip) {
;       float4* s4 = reinterpret_cast<float4*>(Sf + row * SSTR + half * 32);
;       char* prow = Pb + half * 8192 + row * 64;
;       if (MODE == 0) {
;         const int kjb = kj0 + half * 32;
;         float tmax = -1e30f;
; #pragma unroll
;         for (int c = 0; c < 8; ++c) {
;           float4 v = s4[c];
;           float e[4] = {v.x, v.y, v.z, v.w};
; #pragma unroll
;           for (int k = 0; k < 4; ++k) {
;             int kj = kjb + c * 4 + k;
;             bool valid = (kj > row) && (kj <= row + 128);
;             tmax = valid ? fmaxf(tmax, e[k]) : tmax;
;           }
;         }
;         tmax = fmaxf(tmax, __shfl_xor(tmax, 1));
;         float m_new = fmaxf(m_run, tmax);
.LBB0_166:
	s_or_b64 exec, exec, s[6:7]
	s_add_i32 s86, s86, 1
	s_min_i32 s6, s86, s84
	s_add_i32 s6, s6, s83
	s_lshl_b32 s6, s6, 6
	s_add_i32 s6, s6, s85
	s_ashr_i32 s7, s6, 31
	s_add_u32 s6, s6, s81
	s_addc_u32 s7, s7, 0
	s_waitcnt lgkmcnt(0)
	s_barrier
	ds_write_b16 v96, v48
	ds_write_b16_d16_hi v96, v48 offset:64
	ds_write_b16 v96, v49 offset:128
	ds_write_b16_d16_hi v96, v49 offset:192
	ds_write_b16 v96, v50 offset:256
	ds_write_b16_d16_hi v96, v50 offset:320
	ds_write_b16 v96, v51 offset:384
	ds_write_b16_d16_hi v96, v51 offset:448
	s_waitcnt vmcnt(0)
	ds_write_b16 v96, v52 offset:2048
	ds_write_b16_d16_hi v96, v52 offset:2112
	ds_write_b16 v96, v53 offset:2176
	ds_write_b16_d16_hi v96, v53 offset:2240
	ds_write_b16 v96, v54 offset:2304
	ds_write_b16_d16_hi v96, v54 offset:2368
	ds_write_b16 v96, v55 offset:2432
	ds_write_b16_d16_hi v96, v55 offset:2496
	v_lshl_add_u64 v[48:49], s[6:7], 0, v[66:67]
	v_mad_u64_u32 v[52:53], s[10:11], v48, s55, v[76:77]
	v_or_b32_e32 v48, s6, v72
	v_mad_i32_i24 v53, v49, s55, v53
	v_mad_u64_u32 v[54:55], s[10:11], v48, s55, v[78:79]
	v_add_co_u32_e32 v48, vcc, 0x4c000, v52
	v_mad_i32_i24 v55, s7, v160, v55
	s_nop 0
	v_addc_co_u32_e32 v49, vcc, 0, v53, vcc
	global_load_dwordx4 v[60:63], v[48:49], off
	s_nop 0
	global_load_dwordx4 v[48:51], v[54:55], off
	global_load_dwordx4 v[56:59], v[52:53], off
	s_nop 0
	global_load_dwordx4 v[52:55], v[54:55], off offset:64
	s_and_saveexec_b64 s[52:53], s[50:51]
	s_cbranch_execz .LBB0_188
	v_or_b32_e32 v101, s8, v89
	s_movk_i32 s91, 0x80
	ds_read_b128 v[164:167], v90 offset:16384
	ds_read_b128 v[168:171], v90 offset:16400
	ds_read_b128 v[172:175], v90 offset:16416
	ds_read_b128 v[176:179], v90 offset:16432
	ds_read_b128 v[180:183], v90 offset:16448
	ds_read_b128 v[184:187], v90 offset:16464
	ds_read_b128 v[188:191], v90 offset:16480
	ds_read_b128 v[192:195], v90 offset:16496
	v_sub_u32_e32 v102, v80, v101
	v_mov_b32_e32 v83, 0xf149f2ca
	v_mov_b32_e32 v196, v102
	v_add_u32_e32 v197, -1, v102
	v_add_u32_e32 v198, -2, v102
	v_cmp_gt_u32_e32 vcc, s91, v196
	v_cmp_gt_u32_e64 s[92:93], s91, v197
	v_cmp_gt_u32_e64 s[94:95], s91, v198
	s_waitcnt lgkmcnt(7)
	v_cndmask_b32_e32 v164, v83, v164, vcc
	v_cndmask_b32_e64 v165, v83, v165, s[92:93]
	v_cndmask_b32_e64 v166, v83, v166, s[94:95]
	v_add_u32_e32 v196, -3, v102
	v_add_u32_e32 v197, -4, v102
	v_add_u32_e32 v198, -5, v102
	v_cmp_gt_u32_e32 vcc, s91, v196
	v_cmp_gt_u32_e64 s[92:93], s91, v197
	v_cmp_gt_u32_e64 s[94:95], s91, v198
	s_waitcnt lgkmcnt(6)
	v_cndmask_b32_e32 v167, v83, v167, vcc
	v_cndmask_b32_e64 v168, v83, v168, s[92:93]
	v_cndmask_b32_e64 v169, v83, v169, s[94:95]
	v_add_u32_e32 v196, -6, v102
	v_add_u32_e32 v197, -7, v102
	v_add_u32_e32 v198, -8, v102
	v_cmp_gt_u32_e32 vcc, s91, v196
	v_cmp_gt_u32_e64 s[92:93], s91, v197
	v_cmp_gt_u32_e64 s[94:95], s91, v198
	s_waitcnt lgkmcnt(5)
	v_cndmask_b32_e32 v170, v83, v170, vcc
	v_cndmask_b32_e64 v171, v83, v171, s[92:93]
	v_cndmask_b32_e64 v172, v83, v172, s[94:95]
	v_add_u32_e32 v196, -9, v102
	v_add_u32_e32 v197, -10, v102
	v_add_u32_e32 v198, -11, v102
	v_cmp_gt_u32_e32 vcc, s91, v196
	v_cmp_gt_u32_e64 s[92:93], s91, v197
	v_cmp_gt_u32_e64 s[94:95], s91, v198
	v_cndmask_b32_e32 v173, v83, v173, vcc
	v_cndmask_b32_e64 v174, v83, v174, s[92:93]
	v_cndmask_b32_e64 v175, v83, v175, s[94:95]
	v_add_u32_e32 v196, -12, v102
	v_add_u32_e32 v197, -13, v102
	v_add_u32_e32 v198, -14, v102
	v_cmp_gt_u32_e32 vcc, s91, v196
	v_cmp_gt_u32_e64 s[92:93], s91, v197
	v_cmp_gt_u32_e64 s[94:95], s91, v198
	s_waitcnt lgkmcnt(4)
	v_cndmask_b32_e32 v176, v83, v176, vcc
	v_cndmask_b32_e64 v177, v83, v177, s[92:93]
	v_cndmask_b32_e64 v178, v83, v178, s[94:95]
	v_add_u32_e32 v196, -15, v102
	v_add_u32_e32 v197, -16, v102
	v_add_u32_e32 v198, 0xffffffef, v102
	v_cmp_gt_u32_e32 vcc, s91, v196
	v_cmp_gt_u32_e64 s[92:93], s91, v197
	v_cmp_gt_u32_e64 s[94:95], s91, v198
	s_waitcnt lgkmcnt(3)
	v_cndmask_b32_e32 v179, v83, v179, vcc
	v_cndmask_b32_e64 v180, v83, v180, s[92:93]
	v_cndmask_b32_e64 v181, v83, v181, s[94:95]
	v_add_u32_e32 v196, 0xffffffee, v102
	v_add_u32_e32 v197, 0xffffffed, v102
	v_add_u32_e32 v198, 0xffffffec, v102
	v_cmp_gt_u32_e32 vcc, s91, v196
	v_cmp_gt_u32_e64 s[92:93], s91, v197
	v_cmp_gt_u32_e64 s[94:95], s91, v198
	s_waitcnt lgkmcnt(2)
	v_cndmask_b32_e32 v182, v83, v182, vcc
	v_cndmask_b32_e64 v183, v83, v183, s[92:93]
	v_cndmask_b32_e64 v184, v83, v184, s[94:95]
	v_add_u32_e32 v196, 0xffffffeb, v102
	v_add_u32_e32 v197, 0xffffffea, v102
	v_add_u32_e32 v198, 0xffffffe9, v102
	v_cmp_gt_u32_e32 vcc, s91, v196
	v_cmp_gt_u32_e64 s[92:93], s91, v197
	v_cmp_gt_u32_e64 s[94:95], s91, v198
	v_cndmask_b32_e32 v185, v83, v185, vcc
	v_cndmask_b32_e64 v186, v83, v186, s[92:93]
	v_cndmask_b32_e64 v187, v83, v187, s[94:95]
	v_add_u32_e32 v196, 0xffffffe8, v102
	v_add_u32_e32 v197, 0xffffffe7, v102
	v_add_u32_e32 v198, 0xffffffe6, v102
	v_cmp_gt_u32_e32 vcc, s91, v196
	v_cmp_gt_u32_e64 s[92:93], s91, v197
	v_cmp_gt_u32_e64 s[94:95], s91, v198
	s_waitcnt lgkmcnt(1)
	v_cndmask_b32_e32 v188, v83, v188, vcc
	v_cndmask_b32_e64 v189, v83, v189, s[92:93]
	v_cndmask_b32_e64 v190, v83, v190, s[94:95]
	v_add_u32_e32 v196, 0xffffffe5, v102
	v_add_u32_e32 v197, 0xffffffe4, v102
	v_add_u32_e32 v198, 0xffffffe3, v102
	v_cmp_gt_u32_e32 vcc, s91, v196
	v_cmp_gt_u32_e64 s[92:93], s91, v197
	v_cmp_gt_u32_e64 s[94:95], s91, v198
	s_waitcnt lgkmcnt(0)
	v_cndmask_b32_e32 v191, v83, v191, vcc
	v_cndmask_b32_e64 v192, v83, v192, s[92:93]
	v_cndmask_b32_e64 v193, v83, v193, s[94:95]
	v_add_u32_e32 v196, 0xffffffe2, v102
	v_add_u32_e32 v197, 0xffffffe1, v102
	v_cmp_gt_u32_e32 vcc, s91, v196
	v_cmp_gt_u32_e64 s[92:93], s91, v197
	s_nop 0
	v_cndmask_b32_e32 v194, v83, v194, vcc
	v_cndmask_b32_e64 v195, v83, v195, s[92:93]
	v_max3_f32 v164, v164, v165, v166
	v_max3_f32 v167, v167, v168, v169
	v_max3_f32 v170, v170, v171, v172
	v_max3_f32 v173, v173, v174, v175
	v_max3_f32 v176, v176, v177, v178
	v_max3_f32 v179, v179, v180, v181
	v_max3_f32 v182, v182, v183, v184
	v_max3_f32 v185, v185, v186, v187
	v_max3_f32 v188, v188, v189, v190
	v_max3_f32 v191, v191, v192, v193
	v_max_f32_e32 v194, v194, v195
	v_max3_f32 v164, v164, v167, v170
	v_max3_f32 v173, v173, v176, v179
	v_max3_f32 v182, v182, v185, v188
	v_max_f32_e32 v191, v191, v194
	v_max3_f32 v164, v164, v173, v182
	v_max_f32_e32 v164, v164, v191
	v_mov_b32_e32 v82, v164
	v_cmp_lt_i32_e32 vcc, v157, v158
	s_mov_b32 s87, 0
	v_mov_b32_e32 v103, 0
	v_cndmask_b32_e32 v83, v156, v157, vcc
	v_lshlrev_b32_e32 v83, 2, v83
	ds_bpermute_b32 v101, v83, v82
	v_mov_b32_e32 v102, v91
	s_waitcnt lgkmcnt(0)
	v_max3_f32 v82, v87, v82, v101
	v_mov_b32_e32 v101, v93

; template <int DH, int MODE>
; __device__ void attn_item(const Params& p, int layer, int b, int blk, int head, char* smem) {
;     ...
;     V_SCATTER_(vr0, 0);
;     V_SCATTER_(vr1, 1);
;     if (KCH > 2) {
;       V_SCATTER_(vr2, 2);
;       V_SCATTER_(vr3, 3);
;     }
;     KV_LOAD_(it + 1);
;     if (!wskip) {
;       float4* s4 = reinterpret_cast<float4*>(Sf + row * SSTR + half * 32);
;       char* prow = Pb + half * 8192 + row * 64;
;       if (MODE == 0) {
;         const int kjb = kj0 + half * 32;
;         float tmax = -1e30f;
; #pragma unroll
;         for (int c = 0; c < 8; ++c) {
;           float4 v = s4[c];
;           float e[4] = {v.x, v.y, v.z, v.w};
; #pragma unroll
;           for (int k = 0; k < 4; ++k) {
;             int kj = kjb + c * 4 + k;
;             bool valid = (kj > row) && (kj <= row + 128);
;             tmax = valid ? fmaxf(tmax, e[k]) : tmax;
;           }
;         }
;         tmax = fmaxf(tmax, __shfl_xor(tmax, 1));
;         float m_new = fmaxf(m_run, tmax);
.LBB0_487:
	s_or_b64 exec, exec, s[14:15]
	s_add_i32 s89, s89, 1
	s_min_i32 s14, s89, s87
	s_add_i32 s14, s14, s86
	s_lshl_b32 s14, s14, 6
	s_add_i32 s14, s14, s88
	s_ashr_i32 s15, s14, 31
	s_add_u32 s14, s14, s84
	s_addc_u32 s15, s15, 0
	s_waitcnt lgkmcnt(0)
	s_barrier
	ds_write_b16 v96, v48
	ds_write_b16_d16_hi v96, v48 offset:64
	ds_write_b16 v96, v49 offset:128
	ds_write_b16_d16_hi v96, v49 offset:192
	ds_write_b16 v96, v50 offset:256
	ds_write_b16_d16_hi v96, v50 offset:320
	ds_write_b16 v96, v51 offset:384
	ds_write_b16_d16_hi v96, v51 offset:448
	s_waitcnt vmcnt(0)
	ds_write_b16 v96, v52 offset:2048
	ds_write_b16_d16_hi v96, v52 offset:2112
	ds_write_b16 v96, v53 offset:2176
	ds_write_b16_d16_hi v96, v53 offset:2240
	ds_write_b16 v96, v54 offset:2304
	ds_write_b16_d16_hi v96, v54 offset:2368
	ds_write_b16 v96, v55 offset:2432
	ds_write_b16_d16_hi v96, v55 offset:2496
	v_lshl_add_u64 v[48:49], s[14:15], 0, v[66:67]
	v_mad_u64_u32 v[52:53], s[20:21], v48, s63, v[76:77]
	v_or_b32_e32 v48, s14, v72
	v_mad_i32_i24 v53, v49, s63, v53
	v_mad_u64_u32 v[54:55], s[20:21], v48, s63, v[78:79]
	v_add_co_u32_e32 v48, vcc, 0x4c000, v52
	v_mad_i32_i24 v55, s15, v160, v55
	s_nop 0
	v_addc_co_u32_e32 v49, vcc, 0, v53, vcc
	global_load_dwordx4 v[60:63], v[48:49], off
	s_nop 0
	global_load_dwordx4 v[48:51], v[54:55], off
	global_load_dwordx4 v[56:59], v[52:53], off
	s_nop 0
	global_load_dwordx4 v[52:55], v[54:55], off offset:64
	s_and_saveexec_b64 s[54:55], s[52:53]
	s_cbranch_execz .LBB0_509
	v_or_b32_e32 v101, s16, v89
	s_movk_i32 s91, 0x80
	ds_read_b128 v[164:167], v90 offset:16384
	ds_read_b128 v[168:171], v90 offset:16400
	ds_read_b128 v[172:175], v90 offset:16416
	ds_read_b128 v[176:179], v90 offset:16432
	ds_read_b128 v[180:183], v90 offset:16448
	ds_read_b128 v[184:187], v90 offset:16464
	ds_read_b128 v[188:191], v90 offset:16480
	ds_read_b128 v[192:195], v90 offset:16496
	v_sub_u32_e32 v102, v80, v101
	v_mov_b32_e32 v83, 0xf149f2ca
	v_mov_b32_e32 v196, v102
	v_add_u32_e32 v197, -1, v102
	v_add_u32_e32 v198, -2, v102
	v_cmp_gt_u32_e32 vcc, s91, v196
	v_cmp_gt_u32_e64 s[92:93], s91, v197
	v_cmp_gt_u32_e64 s[94:95], s91, v198
	s_waitcnt lgkmcnt(7)
	v_cndmask_b32_e32 v164, v83, v164, vcc
	v_cndmask_b32_e64 v165, v83, v165, s[92:93]
	v_cndmask_b32_e64 v166, v83, v166, s[94:95]
	v_add_u32_e32 v196, -3, v102
	v_add_u32_e32 v197, -4, v102
	v_add_u32_e32 v198, -5, v102
	v_cmp_gt_u32_e32 vcc, s91, v196
	v_cmp_gt_u32_e64 s[92:93], s91, v197
	v_cmp_gt_u32_e64 s[94:95], s91, v198
	s_waitcnt lgkmcnt(6)
	v_cndmask_b32_e32 v167, v83, v167, vcc
	v_cndmask_b32_e64 v168, v83, v168, s[92:93]
	v_cndmask_b32_e64 v169, v83, v169, s[94:95]
	v_add_u32_e32 v196, -6, v102
	v_add_u32_e32 v197, -7, v102
	v_add_u32_e32 v198, -8, v102
	v_cmp_gt_u32_e32 vcc, s91, v196
	v_cmp_gt_u32_e64 s[92:93], s91, v197
	v_cmp_gt_u32_e64 s[94:95], s91, v198
	s_waitcnt lgkmcnt(5)
	v_cndmask_b32_e32 v170, v83, v170, vcc
	v_cndmask_b32_e64 v171, v83, v171, s[92:93]
	v_cndmask_b32_e64 v172, v83, v172, s[94:95]
	v_add_u32_e32 v196, -9, v102
	v_add_u32_e32 v197, -10, v102
	v_add_u32_e32 v198, -11, v102
	v_cmp_gt_u32_e32 vcc, s91, v196
	v_cmp_gt_u32_e64 s[92:93], s91, v197
	v_cmp_gt_u32_e64 s[94:95], s91, v198
	v_cndmask_b32_e32 v173, v83, v173, vcc
	v_cndmask_b32_e64 v174, v83, v174, s[92:93]
	v_cndmask_b32_e64 v175, v83, v175, s[94:95]
	v_add_u32_e32 v196, -12, v102
	v_add_u32_e32 v197, -13, v102
	v_add_u32_e32 v198, -14, v102
	v_cmp_gt_u32_e32 vcc, s91, v196
	v_cmp_gt_u32_e64 s[92:93], s91, v197
	v_cmp_gt_u32_e64 s[94:95], s91, v198
	s_waitcnt lgkmcnt(4)
	v_cndmask_b32_e32 v176, v83, v176, vcc
	v_cndmask_b32_e64 v177, v83, v177, s[92:93]
	v_cndmask_b32_e64 v178, v83, v178, s[94:95]
	v_add_u32_e32 v196, -15, v102
	v_add_u32_e32 v197, -16, v102
	v_add_u32_e32 v198, 0xffffffef, v102
	v_cmp_gt_u32_e32 vcc, s91, v196
	v_cmp_gt_u32_e64 s[92:93], s91, v197
	v_cmp_gt_u32_e64 s[94:95], s91, v198
	s_waitcnt lgkmcnt(3)
	v_cndmask_b32_e32 v179, v83, v179, vcc
	v_cndmask_b32_e64 v180, v83, v180, s[92:93]
	v_cndmask_b32_e64 v181, v83, v181, s[94:95]
	v_add_u32_e32 v196, 0xffffffee, v102
	v_add_u32_e32 v197, 0xffffffed, v102
	v_add_u32_e32 v198, 0xffffffec, v102
	v_cmp_gt_u32_e32 vcc, s91, v196
	v_cmp_gt_u32_e64 s[92:93], s91, v197
	v_cmp_gt_u32_e64 s[94:95], s91, v198
	s_waitcnt lgkmcnt(2)
	v_cndmask_b32_e32 v182, v83, v182, vcc
	v_cndmask_b32_e64 v183, v83, v183, s[92:93]
	v_cndmask_b32_e64 v184, v83, v184, s[94:95]
	v_add_u32_e32 v196, 0xffffffeb, v102
	v_add_u32_e32 v197, 0xffffffea, v102
	v_add_u32_e32 v198, 0xffffffe9, v102
	v_cmp_gt_u32_e32 vcc, s91, v196
	v_cmp_gt_u32_e64 s[92:93], s91, v197
	v_cmp_gt_u32_e64 s[94:95], s91, v198
	v_cndmask_b32_e32 v185, v83, v185, vcc
	v_cndmask_b32_e64 v186, v83, v186, s[92:93]
	v_cndmask_b32_e64 v187, v83, v187, s[94:95]
	v_add_u32_e32 v196, 0xffffffe8, v102
	v_add_u32_e32 v197, 0xffffffe7, v102
	v_add_u32_e32 v198, 0xffffffe6, v102
	v_cmp_gt_u32_e32 vcc, s91, v196
	v_cmp_gt_u32_e64 s[92:93], s91, v197
	v_cmp_gt_u32_e64 s[94:95], s91, v198
	s_waitcnt lgkmcnt(1)
	v_cndmask_b32_e32 v188, v83, v188, vcc
	v_cndmask_b32_e64 v189, v83, v189, s[92:93]
	v_cndmask_b32_e64 v190, v83, v190, s[94:95]
	v_add_u32_e32 v196, 0xffffffe5, v102
	v_add_u32_e32 v197, 0xffffffe4, v102
	v_add_u32_e32 v198, 0xffffffe3, v102
	v_cmp_gt_u32_e32 vcc, s91, v196
	v_cmp_gt_u32_e64 s[92:93], s91, v197
	v_cmp_gt_u32_e64 s[94:95], s91, v198
	s_waitcnt lgkmcnt(0)
	v_cndmask_b32_e32 v191, v83, v191, vcc
	v_cndmask_b32_e64 v192, v83, v192, s[92:93]
	v_cndmask_b32_e64 v193, v83, v193, s[94:95]
	v_add_u32_e32 v196, 0xffffffe2, v102
	v_add_u32_e32 v197, 0xffffffe1, v102
	v_cmp_gt_u32_e32 vcc, s91, v196
	v_cmp_gt_u32_e64 s[92:93], s91, v197
	s_nop 0
	v_cndmask_b32_e32 v194, v83, v194, vcc
	v_cndmask_b32_e64 v195, v83, v195, s[92:93]
	v_max3_f32 v164, v164, v165, v166
	v_max3_f32 v167, v167, v168, v169
	v_max3_f32 v170, v170, v171, v172
	v_max3_f32 v173, v173, v174, v175
	v_max3_f32 v176, v176, v177, v178
	v_max3_f32 v179, v179, v180, v181
	v_max3_f32 v182, v182, v183, v184
	v_max3_f32 v185, v185, v186, v187
	v_max3_f32 v188, v188, v189, v190
	v_max3_f32 v191, v191, v192, v193
	v_max_f32_e32 v194, v194, v195
	v_max3_f32 v164, v164, v167, v170
	v_max3_f32 v173, v173, v176, v179
	v_max3_f32 v182, v182, v185, v188
	v_max_f32_e32 v191, v191, v194
	v_max3_f32 v164, v164, v173, v182
	v_max_f32_e32 v164, v164, v191
	v_mov_b32_e32 v82, v164
	v_cmp_lt_i32_e32 vcc, v157, v158
	s_mov_b32 s90, 0
	v_mov_b32_e32 v103, 0
	v_cndmask_b32_e32 v83, v156, v157, vcc
	v_lshlrev_b32_e32 v83, 2, v83
	ds_bpermute_b32 v101, v83, v82
	v_mov_b32_e32 v102, v91
	s_waitcnt lgkmcnt(0)
	v_max3_f32 v82, v87, v82, v101
	v_mov_b32_e32 v101, v93

; template <int DH, int MODE>
; __device__ void attn_item(const Params& p, int layer, int b, int blk, int head, char* smem) {
;     ...
;     V_SCATTER_(vr0, 0);
;     V_SCATTER_(vr1, 1);
;     if (KCH > 2) {
;       V_SCATTER_(vr2, 2);
;       V_SCATTER_(vr3, 3);
;     }
;     KV_LOAD_(it + 1);
;     if (!wskip) {
;       float4* s4 = reinterpret_cast<float4*>(Sf + row * SSTR + half * 32);
;       char* prow = Pb + half * 8192 + row * 64;
;       if (MODE == 0) {
;         const int kjb = kj0 + half * 32;
;         float tmax = -1e30f;
; #pragma unroll
;         for (int c = 0; c < 8; ++c) {
;           float4 v = s4[c];
;           float e[4] = {v.x, v.y, v.z, v.w};
; #pragma unroll
;           for (int k = 0; k < 4; ++k) {
;             int kj = kjb + c * 4 + k;
;             bool valid = (kj > row) && (kj <= row + 128);
;             tmax = valid ? fmaxf(tmax, e[k]) : tmax;
;           }
;         }
;         tmax = fmaxf(tmax, __shfl_xor(tmax, 1));
;         float m_new = fmaxf(m_run, tmax);
.LBB0_808:
	s_or_b64 exec, exec, s[14:15]
	s_add_i32 s89, s89, 1
	s_min_i32 s14, s89, s87
	s_add_i32 s14, s14, s86
	s_lshl_b32 s14, s14, 6
	s_add_i32 s14, s14, s88
	s_ashr_i32 s15, s14, 31
	s_add_u32 s14, s14, s84
	s_addc_u32 s15, s15, 0
	s_waitcnt lgkmcnt(0)
	s_barrier
	ds_write_b16 v96, v48
	ds_write_b16_d16_hi v96, v48 offset:64
	ds_write_b16 v96, v49 offset:128
	ds_write_b16_d16_hi v96, v49 offset:192
	ds_write_b16 v96, v50 offset:256
	ds_write_b16_d16_hi v96, v50 offset:320
	ds_write_b16 v96, v51 offset:384
	ds_write_b16_d16_hi v96, v51 offset:448
	s_waitcnt vmcnt(0)
	ds_write_b16 v96, v52 offset:2048
	ds_write_b16_d16_hi v96, v52 offset:2112
	ds_write_b16 v96, v53 offset:2176
	ds_write_b16_d16_hi v96, v53 offset:2240
	ds_write_b16 v96, v54 offset:2304
	ds_write_b16_d16_hi v96, v54 offset:2368
	ds_write_b16 v96, v55 offset:2432
	ds_write_b16_d16_hi v96, v55 offset:2496
	v_lshl_add_u64 v[48:49], s[14:15], 0, v[66:67]
	v_mad_u64_u32 v[52:53], s[20:21], v48, s45, v[76:77]
	v_or_b32_e32 v48, s14, v72
	v_mad_i32_i24 v53, v49, s45, v53
	v_mad_u64_u32 v[54:55], s[20:21], v48, s45, v[78:79]
	v_add_co_u32_e32 v48, vcc, 0x4c000, v52
	v_mad_i32_i24 v55, s15, v160, v55
	s_nop 0
	v_addc_co_u32_e32 v49, vcc, 0, v53, vcc
	global_load_dwordx4 v[60:63], v[48:49], off
	s_nop 0
	global_load_dwordx4 v[48:51], v[54:55], off
	global_load_dwordx4 v[56:59], v[52:53], off
	s_nop 0
	global_load_dwordx4 v[52:55], v[54:55], off offset:64
	s_and_saveexec_b64 s[52:53], s[50:51]
	s_cbranch_execz .LBB0_830
	v_or_b32_e32 v101, s16, v89
	s_movk_i32 s91, 0x80
	ds_read_b128 v[164:167], v90 offset:16384
	ds_read_b128 v[168:171], v90 offset:16400
	ds_read_b128 v[172:175], v90 offset:16416
	ds_read_b128 v[176:179], v90 offset:16432
	ds_read_b128 v[180:183], v90 offset:16448
	ds_read_b128 v[184:187], v90 offset:16464
	ds_read_b128 v[188:191], v90 offset:16480
	ds_read_b128 v[192:195], v90 offset:16496
	v_sub_u32_e32 v102, v80, v101
	v_mov_b32_e32 v83, 0xf149f2ca
	v_mov_b32_e32 v196, v102
	v_add_u32_e32 v197, -1, v102
	v_add_u32_e32 v198, -2, v102
	v_cmp_gt_u32_e32 vcc, s91, v196
	v_cmp_gt_u32_e64 s[92:93], s91, v197
	v_cmp_gt_u32_e64 s[94:95], s91, v198
	s_waitcnt lgkmcnt(7)
	v_cndmask_b32_e32 v164, v83, v164, vcc
	v_cndmask_b32_e64 v165, v83, v165, s[92:93]
	v_cndmask_b32_e64 v166, v83, v166, s[94:95]
	v_add_u32_e32 v196, -3, v102
	v_add_u32_e32 v197, -4, v102
	v_add_u32_e32 v198, -5, v102
	v_cmp_gt_u32_e32 vcc, s91, v196
	v_cmp_gt_u32_e64 s[92:93], s91, v197
	v_cmp_gt_u32_e64 s[94:95], s91, v198
	s_waitcnt lgkmcnt(6)
	v_cndmask_b32_e32 v167, v83, v167, vcc
	v_cndmask_b32_e64 v168, v83, v168, s[92:93]
	v_cndmask_b32_e64 v169, v83, v169, s[94:95]
	v_add_u32_e32 v196, -6, v102
	v_add_u32_e32 v197, -7, v102
	v_add_u32_e32 v198, -8, v102
	v_cmp_gt_u32_e32 vcc, s91, v196
	v_cmp_gt_u32_e64 s[92:93], s91, v197
	v_cmp_gt_u32_e64 s[94:95], s91, v198
	s_waitcnt lgkmcnt(5)
	v_cndmask_b32_e32 v170, v83, v170, vcc
	v_cndmask_b32_e64 v171, v83, v171, s[92:93]
	v_cndmask_b32_e64 v172, v83, v172, s[94:95]
	v_add_u32_e32 v196, -9, v102
	v_add_u32_e32 v197, -10, v102
	v_add_u32_e32 v198, -11, v102
	v_cmp_gt_u32_e32 vcc, s91, v196
	v_cmp_gt_u32_e64 s[92:93], s91, v197
	v_cmp_gt_u32_e64 s[94:95], s91, v198
	v_cndmask_b32_e32 v173, v83, v173, vcc
	v_cndmask_b32_e64 v174, v83, v174, s[92:93]
	v_cndmask_b32_e64 v175, v83, v175, s[94:95]
	v_add_u32_e32 v196, -12, v102
	v_add_u32_e32 v197, -13, v102
	v_add_u32_e32 v198, -14, v102
	v_cmp_gt_u32_e32 vcc, s91, v196
	v_cmp_gt_u32_e64 s[92:93], s91, v197
	v_cmp_gt_u32_e64 s[94:95], s91, v198
	s_waitcnt lgkmcnt(4)
	v_cndmask_b32_e32 v176, v83, v176, vcc
	v_cndmask_b32_e64 v177, v83, v177, s[92:93]
	v_cndmask_b32_e64 v178, v83, v178, s[94:95]
	v_add_u32_e32 v196, -15, v102
	v_add_u32_e32 v197, -16, v102
	v_add_u32_e32 v198, 0xffffffef, v102
	v_cmp_gt_u32_e32 vcc, s91, v196
	v_cmp_gt_u32_e64 s[92:93], s91, v197
	v_cmp_gt_u32_e64 s[94:95], s91, v198
	s_waitcnt lgkmcnt(3)
	v_cndmask_b32_e32 v179, v83, v179, vcc
	v_cndmask_b32_e64 v180, v83, v180, s[92:93]
	v_cndmask_b32_e64 v181, v83, v181, s[94:95]
	v_add_u32_e32 v196, 0xffffffee, v102
	v_add_u32_e32 v197, 0xffffffed, v102
	v_add_u32_e32 v198, 0xffffffec, v102
	v_cmp_gt_u32_e32 vcc, s91, v196
	v_cmp_gt_u32_e64 s[92:93], s91, v197
	v_cmp_gt_u32_e64 s[94:95], s91, v198
	s_waitcnt lgkmcnt(2)
	v_cndmask_b32_e32 v182, v83, v182, vcc
	v_cndmask_b32_e64 v183, v83, v183, s[92:93]
	v_cndmask_b32_e64 v184, v83, v184, s[94:95]
	v_add_u32_e32 v196, 0xffffffeb, v102
	v_add_u32_e32 v197, 0xffffffea, v102
	v_add_u32_e32 v198, 0xffffffe9, v102
	v_cmp_gt_u32_e32 vcc, s91, v196
	v_cmp_gt_u32_e64 s[92:93], s91, v197
	v_cmp_gt_u32_e64 s[94:95], s91, v198
	v_cndmask_b32_e32 v185, v83, v185, vcc
	v_cndmask_b32_e64 v186, v83, v186, s[92:93]
	v_cndmask_b32_e64 v187, v83, v187, s[94:95]
	v_add_u32_e32 v196, 0xffffffe8, v102
	v_add_u32_e32 v197, 0xffffffe7, v102
	v_add_u32_e32 v198, 0xffffffe6, v102
	v_cmp_gt_u32_e32 vcc, s91, v196
	v_cmp_gt_u32_e64 s[92:93], s91, v197
	v_cmp_gt_u32_e64 s[94:95], s91, v198
	s_waitcnt lgkmcnt(1)
	v_cndmask_b32_e32 v188, v83, v188, vcc
	v_cndmask_b32_e64 v189, v83, v189, s[92:93]
	v_cndmask_b32_e64 v190, v83, v190, s[94:95]
	v_add_u32_e32 v196, 0xffffffe5, v102
	v_add_u32_e32 v197, 0xffffffe4, v102
	v_add_u32_e32 v198, 0xffffffe3, v102
	v_cmp_gt_u32_e32 vcc, s91, v196
	v_cmp_gt_u32_e64 s[92:93], s91, v197
	v_cmp_gt_u32_e64 s[94:95], s91, v198
	s_waitcnt lgkmcnt(0)
	v_cndmask_b32_e32 v191, v83, v191, vcc
	v_cndmask_b32_e64 v192, v83, v192, s[92:93]
	v_cndmask_b32_e64 v193, v83, v193, s[94:95]
	v_add_u32_e32 v196, 0xffffffe2, v102
	v_add_u32_e32 v197, 0xffffffe1, v102
	v_cmp_gt_u32_e32 vcc, s91, v196
	v_cmp_gt_u32_e64 s[92:93], s91, v197
	s_nop 0
	v_cndmask_b32_e32 v194, v83, v194, vcc
	v_cndmask_b32_e64 v195, v83, v195, s[92:93]
	v_max3_f32 v164, v164, v165, v166
	v_max3_f32 v167, v167, v168, v169
	v_max3_f32 v170, v170, v171, v172
	v_max3_f32 v173, v173, v174, v175
	v_max3_f32 v176, v176, v177, v178
	v_max3_f32 v179, v179, v180, v181
	v_max3_f32 v182, v182, v183, v184
	v_max3_f32 v185, v185, v186, v187
	v_max3_f32 v188, v188, v189, v190
	v_max3_f32 v191, v191, v192, v193
	v_max_f32_e32 v194, v194, v195
	v_max3_f32 v164, v164, v167, v170
	v_max3_f32 v173, v173, v176, v179
	v_max3_f32 v182, v182, v185, v188
	v_max_f32_e32 v191, v191, v194
	v_max3_f32 v164, v164, v173, v182
	v_max_f32_e32 v164, v164, v191
	v_mov_b32_e32 v82, v164
	v_cmp_lt_i32_e32 vcc, v157, v158
	s_mov_b32 s90, 0
	v_mov_b32_e32 v103, 0
	v_cndmask_b32_e32 v83, v156, v157, vcc
	v_lshlrev_b32_e32 v83, 2, v83
	ds_bpermute_b32 v101, v83, v82
	v_mov_b32_e32 v102, v91
	s_waitcnt lgkmcnt(0)
	v_max3_f32 v82, v87, v82, v101
	v_mov_b32_e32 v101, v93

; template <int DH, int MODE>
; __device__ void attn_item(const Params& p, int layer, int b, int blk, int head, char* smem) {
;     ...
;     V_SCATTER_(vr0, 0);
;     V_SCATTER_(vr1, 1);
;     if (KCH > 2) {
;       V_SCATTER_(vr2, 2);
;       V_SCATTER_(vr3, 3);
;     }
;     KV_LOAD_(it + 1);
;     if (!wskip) {
;       float4* s4 = reinterpret_cast<float4*>(Sf + row * SSTR + half * 32);
;       char* prow = Pb + half * 8192 + row * 64;
;       if (MODE == 0) {
;         const int kjb = kj0 + half * 32;
;         float tmax = -1e30f;
; #pragma unroll
;         for (int c = 0; c < 8; ++c) {
;           float4 v = s4[c];
;           float e[4] = {v.x, v.y, v.z, v.w};
; #pragma unroll
;           for (int k = 0; k < 4; ++k) {
;             int kj = kjb + c * 4 + k;
;             bool valid = (kj > row) && (kj <= row + 128);
;             tmax = valid ? fmaxf(tmax, e[k]) : tmax;
;           }
;         }
;         tmax = fmaxf(tmax, __shfl_xor(tmax, 1));
;         float m_new = fmaxf(m_run, tmax);
.LBB0_1129:
	s_or_b64 exec, exec, s[8:9]
	s_add_i32 s82, s82, 1
	s_min_i32 s8, s82, s80
	s_add_i32 s8, s8, s79
	s_lshl_b32 s8, s8, 6
	s_add_i32 s8, s8, s81
	s_ashr_i32 s9, s8, 31
	s_add_u32 s8, s8, s77
	s_addc_u32 s9, s9, 0
	s_waitcnt lgkmcnt(0)
	s_barrier
	ds_write_b16 v96, v48
	ds_write_b16_d16_hi v96, v48 offset:64
	ds_write_b16 v96, v49 offset:128
	ds_write_b16_d16_hi v96, v49 offset:192
	ds_write_b16 v96, v50 offset:256
	ds_write_b16_d16_hi v96, v50 offset:320
	ds_write_b16 v96, v51 offset:384
	ds_write_b16_d16_hi v96, v51 offset:448
	s_waitcnt vmcnt(0)
	ds_write_b16 v96, v52 offset:2048
	ds_write_b16_d16_hi v96, v52 offset:2112
	ds_write_b16 v96, v53 offset:2176
	ds_write_b16_d16_hi v96, v53 offset:2240
	ds_write_b16 v96, v54 offset:2304
	ds_write_b16_d16_hi v96, v54 offset:2368
	ds_write_b16 v96, v55 offset:2432
	ds_write_b16_d16_hi v96, v55 offset:2496
	v_lshl_add_u64 v[48:49], s[8:9], 0, v[66:67]
	v_mad_u64_u32 v[52:53], s[12:13], v48, s39, v[76:77]
	v_or_b32_e32 v48, s8, v72
	v_mad_i32_i24 v53, v49, s39, v53
	v_mad_u64_u32 v[54:55], s[12:13], v48, s39, v[78:79]
	v_add_co_u32_e32 v48, vcc, 0x4c000, v52
	v_mad_i32_i24 v55, s9, v160, v55
	s_nop 0
	v_addc_co_u32_e32 v49, vcc, 0, v53, vcc
	global_load_dwordx4 v[60:63], v[48:49], off
	s_nop 0
	global_load_dwordx4 v[48:51], v[54:55], off
	global_load_dwordx4 v[56:59], v[52:53], off
	s_nop 0
	global_load_dwordx4 v[52:55], v[54:55], off offset:64
	s_and_saveexec_b64 s[46:47], s[44:45]
	s_cbranch_execz .LBB0_1151
	v_or_b32_e32 v101, s10, v89
	s_movk_i32 s91, 0x80
	ds_read_b128 v[164:167], v90 offset:16384
	ds_read_b128 v[168:171], v90 offset:16400
	ds_read_b128 v[172:175], v90 offset:16416
	ds_read_b128 v[176:179], v90 offset:16432
	ds_read_b128 v[180:183], v90 offset:16448
	ds_read_b128 v[184:187], v90 offset:16464
	ds_read_b128 v[188:191], v90 offset:16480
	ds_read_b128 v[192:195], v90 offset:16496
	v_sub_u32_e32 v102, v80, v101
	v_mov_b32_e32 v83, 0xf149f2ca
	v_mov_b32_e32 v196, v102
	v_add_u32_e32 v197, -1, v102
	v_add_u32_e32 v198, -2, v102
	v_cmp_gt_u32_e32 vcc, s91, v196
	v_cmp_gt_u32_e64 s[92:93], s91, v197
	v_cmp_gt_u32_e64 s[94:95], s91, v198
	s_waitcnt lgkmcnt(7)
	v_cndmask_b32_e32 v164, v83, v164, vcc
	v_cndmask_b32_e64 v165, v83, v165, s[92:93]
	v_cndmask_b32_e64 v166, v83, v166, s[94:95]
	v_add_u32_e32 v196, -3, v102
	v_add_u32_e32 v197, -4, v102
	v_add_u32_e32 v198, -5, v102
	v_cmp_gt_u32_e32 vcc, s91, v196
	v_cmp_gt_u32_e64 s[92:93], s91, v197
	v_cmp_gt_u32_e64 s[94:95], s91, v198
	s_waitcnt lgkmcnt(6)
	v_cndmask_b32_e32 v167, v83, v167, vcc
	v_cndmask_b32_e64 v168, v83, v168, s[92:93]
	v_cndmask_b32_e64 v169, v83, v169, s[94:95]
	v_add_u32_e32 v196, -6, v102
	v_add_u32_e32 v197, -7, v102
	v_add_u32_e32 v198, -8, v102
	v_cmp_gt_u32_e32 vcc, s91, v196
	v_cmp_gt_u32_e64 s[92:93], s91, v197
	v_cmp_gt_u32_e64 s[94:95], s91, v198
	s_waitcnt lgkmcnt(5)
	v_cndmask_b32_e32 v170, v83, v170, vcc
	v_cndmask_b32_e64 v171, v83, v171, s[92:93]
	v_cndmask_b32_e64 v172, v83, v172, s[94:95]
	v_add_u32_e32 v196, -9, v102
	v_add_u32_e32 v197, -10, v102
	v_add_u32_e32 v198, -11, v102
	v_cmp_gt_u32_e32 vcc, s91, v196
	v_cmp_gt_u32_e64 s[92:93], s91, v197
	v_cmp_gt_u32_e64 s[94:95], s91, v198
	v_cndmask_b32_e32 v173, v83, v173, vcc
	v_cndmask_b32_e64 v174, v83, v174, s[92:93]
	v_cndmask_b32_e64 v175, v83, v175, s[94:95]
	v_add_u32_e32 v196, -12, v102
	v_add_u32_e32 v197, -13, v102
	v_add_u32_e32 v198, -14, v102
	v_cmp_gt_u32_e32 vcc, s91, v196
	v_cmp_gt_u32_e64 s[92:93], s91, v197
	v_cmp_gt_u32_e64 s[94:95], s91, v198
	s_waitcnt lgkmcnt(4)
	v_cndmask_b32_e32 v176, v83, v176, vcc
	v_cndmask_b32_e64 v177, v83, v177, s[92:93]
	v_cndmask_b32_e64 v178, v83, v178, s[94:95]
	v_add_u32_e32 v196, -15, v102
	v_add_u32_e32 v197, -16, v102
	v_add_u32_e32 v198, 0xffffffef, v102
	v_cmp_gt_u32_e32 vcc, s91, v196
	v_cmp_gt_u32_e64 s[92:93], s91, v197
	v_cmp_gt_u32_e64 s[94:95], s91, v198
	s_waitcnt lgkmcnt(3)
	v_cndmask_b32_e32 v179, v83, v179, vcc
	v_cndmask_b32_e64 v180, v83, v180, s[92:93]
	v_cndmask_b32_e64 v181, v83, v181, s[94:95]
	v_add_u32_e32 v196, 0xffffffee, v102
	v_add_u32_e32 v197, 0xffffffed, v102
	v_add_u32_e32 v198, 0xffffffec, v102
	v_cmp_gt_u32_e32 vcc, s91, v196
	v_cmp_gt_u32_e64 s[92:93], s91, v197
	v_cmp_gt_u32_e64 s[94:95], s91, v198
	s_waitcnt lgkmcnt(2)
	v_cndmask_b32_e32 v182, v83, v182, vcc
	v_cndmask_b32_e64 v183, v83, v183, s[92:93]
	v_cndmask_b32_e64 v184, v83, v184, s[94:95]
	v_add_u32_e32 v196, 0xffffffeb, v102
	v_add_u32_e32 v197, 0xffffffea, v102
	v_add_u32_e32 v198, 0xffffffe9, v102
	v_cmp_gt_u32_e32 vcc, s91, v196
	v_cmp_gt_u32_e64 s[92:93], s91, v197
	v_cmp_gt_u32_e64 s[94:95], s91, v198
	v_cndmask_b32_e32 v185, v83, v185, vcc
	v_cndmask_b32_e64 v186, v83, v186, s[92:93]
	v_cndmask_b32_e64 v187, v83, v187, s[94:95]
	v_add_u32_e32 v196, 0xffffffe8, v102
	v_add_u32_e32 v197, 0xffffffe7, v102
	v_add_u32_e32 v198, 0xffffffe6, v102
	v_cmp_gt_u32_e32 vcc, s91, v196
	v_cmp_gt_u32_e64 s[92:93], s91, v197
	v_cmp_gt_u32_e64 s[94:95], s91, v198
	s_waitcnt lgkmcnt(1)
	v_cndmask_b32_e32 v188, v83, v188, vcc
	v_cndmask_b32_e64 v189, v83, v189, s[92:93]
	v_cndmask_b32_e64 v190, v83, v190, s[94:95]
	v_add_u32_e32 v196, 0xffffffe5, v102
	v_add_u32_e32 v197, 0xffffffe4, v102
	v_add_u32_e32 v198, 0xffffffe3, v102
	v_cmp_gt_u32_e32 vcc, s91, v196
	v_cmp_gt_u32_e64 s[92:93], s91, v197
	v_cmp_gt_u32_e64 s[94:95], s91, v198
	s_waitcnt lgkmcnt(0)
	v_cndmask_b32_e32 v191, v83, v191, vcc
	v_cndmask_b32_e64 v192, v83, v192, s[92:93]
	v_cndmask_b32_e64 v193, v83, v193, s[94:95]
	v_add_u32_e32 v196, 0xffffffe2, v102
	v_add_u32_e32 v197, 0xffffffe1, v102
	v_cmp_gt_u32_e32 vcc, s91, v196
	v_cmp_gt_u32_e64 s[92:93], s91, v197
	s_nop 0
	v_cndmask_b32_e32 v194, v83, v194, vcc
	v_cndmask_b32_e64 v195, v83, v195, s[92:93]
	v_max3_f32 v164, v164, v165, v166
	v_max3_f32 v167, v167, v168, v169
	v_max3_f32 v170, v170, v171, v172
	v_max3_f32 v173, v173, v174, v175
	v_max3_f32 v176, v176, v177, v178
	v_max3_f32 v179, v179, v180, v181
	v_max3_f32 v182, v182, v183, v184
	v_max3_f32 v185, v185, v186, v187
	v_max3_f32 v188, v188, v189, v190
	v_max3_f32 v191, v191, v192, v193
	v_max_f32_e32 v194, v194, v195
	v_max3_f32 v164, v164, v167, v170
	v_max3_f32 v173, v173, v176, v179
	v_max3_f32 v182, v182, v185, v188
	v_max_f32_e32 v191, v191, v194
	v_max3_f32 v164, v164, v173, v182
	v_max_f32_e32 v164, v164, v191
	v_mov_b32_e32 v82, v164
	v_cmp_lt_i32_e32 vcc, v157, v158
	s_mov_b32 s83, 0
	v_mov_b32_e32 v103, 0
	v_cndmask_b32_e32 v83, v156, v157, vcc
	v_lshlrev_b32_e32 v83, 2, v83
	ds_bpermute_b32 v101, v83, v82
	v_mov_b32_e32 v102, v91
	s_waitcnt lgkmcnt(0)
	v_max3_f32 v82, v87, v82, v101
	v_mov_b32_e32 v101, v93
